# P3: 43 pairs of f32->bf16 RNE bit-trick conversions replaced by v_cvt_pk_bf16_f32 + ds_write_b16 lo/hi (fewer VALU ops in the VALU-bound conv step)
# speedup vs baseline: 1.0059x; 1.0059x over previous
.LBB0_212:
	s_or_b64 exec, exec, s[78:79]
	v_ashrrev_i32_e32 v24, 6, v36
	v_xor_b32_e32 v24, v24, v27
	v_and_b32_e32 v25, 7, v29
	v_lshl_or_b32 v25, v24, 3, v25
	v_and_b32_e32 v3, 0x7ffffff0, v29
	v_and_b32_e32 v5, 3, v29
	v_lshlrev_b32_e32 v7, 1, v29
	v_and_b32_e32 v24, 8, v29
	v_lshlrev_b32_e32 v29, 1, v25
	v_mul_f32_e32 v25, 0xbfb8aa3b, v22
	v_exp_f32_e32 v25, v25
	v_and_or_b32 v3, v7, 8, v3
	v_lshlrev_b32_e32 v3, 1, v3
	v_xor_b32_e32 v3, v30, v3
	v_add_f32_e32 v25, 1.0, v25
	v_rcp_f32_e32 v25, v25
	v_lshlrev_b32_e32 v5, 1, v5
	v_add3_u32 v7, 0, v3, v5
	v_sub_f32_e32 v3, v37, v31
	v_mul_f32_e32 v25, v22, v25
	v_mul_f32_e32 v22, 0xbfb8aa3b, v23
	v_exp_f32_e32 v22, v22
	v_mul_f32_e32 v3, 0x3fb8aa3b, v3
	v_exp_f32_e32 v5, v3
	v_mul_f32_e32 v3, v26, v46
	v_add_f32_e32 v22, 1.0, v22
	v_rcp_f32_e32 v22, v22
	s_nop 0
	v_mul_f32_e32 v30, v23, v22
	v_mul_f32_e32 v22, 0xbfb8aa3b, v18
	v_exp_f32_e32 v22, v22
	v_mul_f32_e32 v50, v30, v30
	v_fmac_f32_e32 v50, v25, v25
	v_mul_f32_e32 v23, 0xbfb8aa3b, v21
	v_add_f32_e32 v22, 1.0, v22
	v_rcp_f32_e32 v22, v22
	v_exp_f32_e32 v23, v23
	v_mul_f32_e32 v31, v18, v22
	v_mul_f32_e32 v18, 0xbfb8aa3b, v19
	v_exp_f32_e32 v18, v18
	v_fmac_f32_e32 v50, v31, v31
	v_mul_f32_e32 v22, 0xbfb8aa3b, v20
	v_exp_f32_e32 v22, v22
	v_add_f32_e32 v18, 1.0, v18
	v_rcp_f32_e32 v18, v18
	v_add_f32_e32 v23, 1.0, v23
	v_add_f32_e32 v22, 1.0, v22
	v_rcp_f32_e32 v22, v22
	v_mul_f32_e32 v37, v19, v18
	v_mul_f32_e32 v18, 0xbfb8aa3b, v16
	v_exp_f32_e32 v18, v18
	v_mul_f32_e32 v19, 0xbfb8aa3b, v13
	v_exp_f32_e32 v19, v19
	v_fmac_f32_e32 v50, v37, v37
	v_add_f32_e32 v18, 1.0, v18
	v_rcp_f32_e32 v18, v18
	v_add_f32_e32 v19, 1.0, v19
	v_rcp_f32_e32 v19, v19
	v_rcp_f32_e32 v23, v23
	v_mul_f32_e32 v46, v16, v18
	v_mul_f32_e32 v16, 0xbfb8aa3b, v17
	v_exp_f32_e32 v16, v16
	v_mul_f32_e32 v18, 0xbfb8aa3b, v12
	v_exp_f32_e32 v18, v18
	v_fmac_f32_e32 v50, v46, v46
	v_add_f32_e32 v16, 1.0, v16
	v_rcp_f32_e32 v16, v16
	v_add_f32_e32 v18, 1.0, v18
	v_rcp_f32_e32 v18, v18
	v_mul_f32_e32 v47, v17, v16
	v_mul_f32_e32 v16, 0xbfb8aa3b, v14
	v_exp_f32_e32 v16, v16
	v_mul_f32_e32 v17, 0xbfb8aa3b, v11
	v_exp_f32_e32 v17, v17
	v_fmac_f32_e32 v50, v47, v47
	v_add_f32_e32 v16, 1.0, v16
	v_rcp_f32_e32 v16, v16
	v_add_f32_e32 v17, 1.0, v17
	v_rcp_f32_e32 v17, v17
	v_pk_mul_f32 v[12:13], v[12:13], v[18:19]
	v_mul_f32_e32 v48, v14, v16
	v_mul_f32_e32 v14, 0xbfb8aa3b, v15
	v_exp_f32_e32 v14, v14
	v_mul_f32_e32 v16, 0xbfb8aa3b, v10
	v_exp_f32_e32 v16, v16
	v_fmac_f32_e32 v50, v48, v48
	v_add_f32_e32 v14, 1.0, v14
	v_rcp_f32_e32 v14, v14
	v_add_f32_e32 v16, 1.0, v16
	v_rcp_f32_e32 v16, v16
	v_mul_f32_e32 v49, v15, v14
	v_mul_f32_e32 v14, 0xbfb8aa3b, v8
	v_mul_f32_e32 v15, 0xbfb8aa3b, v9
	v_exp_f32_e32 v14, v14
	v_exp_f32_e32 v15, v15
	v_fmac_f32_e32 v50, v49, v49
	v_pk_mul_f32 v[10:11], v[10:11], v[16:17]
	v_add_f32_e32 v14, 1.0, v14
	v_add_f32_e32 v15, 1.0, v15
	v_rcp_f32_e32 v14, v14
	v_rcp_f32_e32 v15, v15
	s_nop 0
	v_pk_mul_f32 v[8:9], v[8:9], v[14:15]
	s_nop 0
	v_pk_mul_f32 v[14:15], v[8:9], v[8:9]
	s_nop 0
	v_add_f32_e32 v14, v50, v14
	v_add_f32_e32 v50, v14, v15
	v_pk_mul_f32 v[14:15], v[10:11], v[10:11]
	s_nop 0
	v_add_f32_e32 v14, v50, v14
	v_add_f32_e32 v16, v14, v15
	v_pk_mul_f32 v[14:15], v[12:13], v[12:13]
	s_nop 0
	v_add_f32_e32 v14, v16, v14
	v_add_f32_e32 v18, v14, v15
	v_pk_mul_f32 v[14:15], v[20:21], v[22:23]
	s_nop 0
	v_pk_mul_f32 v[16:17], v[14:15], v[14:15]
	s_nop 0
	v_add_f32_e32 v16, v18, v16
	v_add_f32_e32 v16, v16, v17
	ds_bpermute_b32 v17, v45, v16
	s_waitcnt lgkmcnt(0)
	v_add_f32_e32 v16, v16, v17
	ds_bpermute_b32 v17, v44, v16
	s_waitcnt lgkmcnt(0)
	v_add_f32_e32 v16, v16, v17
	ds_bpermute_b32 v17, v43, v16
	s_waitcnt lgkmcnt(0)
	v_add_f32_e32 v16, v16, v17
	v_add_f32_e32 v16, 0x358637bd, v16
	v_cmp_gt_f32_e32 vcc, s85, v16
	v_mul_f32_e32 v17, 0x4b800000, v16
	s_nop 0
	v_cndmask_b32_e32 v16, v16, v17, vcc
	v_rsq_f32_e32 v16, v16
	s_nop 0
	v_mul_f32_e32 v17, 0x45800000, v16
	v_cndmask_b32_e32 v16, v16, v17, vcc
	v_mul_f32_e32 v17, v16, v15
	v_mul_f32_e32 v18, v16, v14
	v_mul_f32_e32 v19, v16, v13
	v_mul_f32_e32 v20, v16, v12
	v_mul_f32_e32 v21, v16, v11
	v_mul_f32_e32 v22, v16, v10
	v_mul_f32_e32 v23, v16, v9
	v_mul_f32_e32 v43, v16, v8
	v_mul_f32_e32 v44, v16, v49
	v_mul_f32_e32 v45, v16, v48
	v_mul_f32_e32 v47, v16, v47
	v_mul_f32_e32 v46, v16, v46
	v_mul_f32_e32 v37, v16, v37
	v_mul_f32_e32 v31, v16, v31
	v_mul_f32_e32 v30, v16, v30
	v_mul_f32_e32 v16, v16, v25
	v_cvt_pk_bf16_f32 v8, v16, v30
	v_cvt_pk_bf16_f32 v9, v31, v37
	v_cvt_pk_bf16_f32 v10, v46, v47
	v_cvt_pk_bf16_f32 v11, v45, v44
	v_cvt_pk_bf16_f32 v12, v43, v23
	v_cvt_pk_bf16_f32 v13, v22, v21
	v_cvt_pk_bf16_f32 v14, v20, v19
	v_cvt_pk_bf16_f32 v15, v18, v17
	ds_write_b128 v42, v[8:11]
	ds_write_b128 v42, v[12:15] offset:16
	v_mul_f32_e32 v8, v5, v16
	v_mul_u32_u24_e32 v9, 0x480, v27
	v_lshlrev_b32_e32 v9, 1, v9
	v_add3_u32 v7, v7, v24, v9
	v_mul_f32_e32 v10, v3, v16
	v_cvt_pk_bf16_f32 v8, v8, v10
	ds_write_b16 v7, v8 offset:34816
	v_add3_u32 v9, s88, v29, v9
	ds_write_b16_d16_hi v9, v8
	v_mul_f32_e32 v8, v5, v30
	v_mul_f32_e32 v10, v3, v30
	v_cvt_pk_bf16_f32 v8, v8, v10
	ds_write_b16 v7, v8 offset:34960
	ds_write_b16_d16_hi v9, v8 offset:144
	v_mul_f32_e32 v8, v5, v31
	v_mul_f32_e32 v10, v3, v31
	v_cvt_pk_bf16_f32 v8, v8, v10
	ds_write_b16 v7, v8 offset:35104
	ds_write_b16_d16_hi v9, v8 offset:288
	v_mul_f32_e32 v8, v5, v37
	v_mul_f32_e32 v10, v3, v37
	v_cvt_pk_bf16_f32 v8, v8, v10
	ds_write_b16 v7, v8 offset:35248
	ds_write_b16_d16_hi v9, v8 offset:432
	v_mul_f32_e32 v8, v5, v46
	v_mul_f32_e32 v10, v3, v46
	v_cvt_pk_bf16_f32 v8, v8, v10
	ds_write_b16 v7, v8 offset:35392
	ds_write_b16_d16_hi v9, v8 offset:576
	v_mul_f32_e32 v8, v5, v47
	v_mul_f32_e32 v10, v3, v47
	v_cvt_pk_bf16_f32 v8, v8, v10
	ds_write_b16 v7, v8 offset:35536
	ds_write_b16_d16_hi v9, v8 offset:720
	v_mul_f32_e32 v8, v5, v45
	v_mul_f32_e32 v10, v3, v45
	v_cvt_pk_bf16_f32 v8, v8, v10
	ds_write_b16 v7, v8 offset:35680
	ds_write_b16_d16_hi v9, v8 offset:864
	v_mul_f32_e32 v8, v5, v44
	v_mul_f32_e32 v10, v3, v44
	v_cvt_pk_bf16_f32 v8, v8, v10
	ds_write_b16 v7, v8 offset:35824
	ds_write_b16_d16_hi v9, v8 offset:1008
	v_mul_f32_e32 v8, v5, v43
	v_mul_f32_e32 v10, v3, v43
	v_cvt_pk_bf16_f32 v8, v8, v10
	ds_write_b16 v7, v8 offset:35968
	ds_write_b16_d16_hi v9, v8 offset:1152
	v_mul_f32_e32 v8, v5, v23
	v_mul_f32_e32 v10, v3, v23
	v_cvt_pk_bf16_f32 v8, v8, v10
	ds_write_b16 v7, v8 offset:36112
	ds_write_b16_d16_hi v9, v8 offset:1296
	v_mul_f32_e32 v8, v5, v22
	v_mul_f32_e32 v10, v3, v22
	v_cvt_pk_bf16_f32 v8, v8, v10
	ds_write_b16 v7, v8 offset:36256
	ds_write_b16_d16_hi v9, v8 offset:1440
	v_mul_f32_e32 v8, v5, v21
	v_mul_f32_e32 v10, v3, v21
	v_cvt_pk_bf16_f32 v8, v8, v10
	ds_write_b16 v7, v8 offset:36400
	ds_write_b16_d16_hi v9, v8 offset:1584
	v_mul_f32_e32 v8, v5, v20
	v_mul_f32_e32 v10, v3, v20
	v_cvt_pk_bf16_f32 v8, v8, v10
	ds_write_b16 v7, v8 offset:36544
	ds_write_b16_d16_hi v9, v8 offset:1728
	v_mul_f32_e32 v8, v5, v19
	v_mul_f32_e32 v10, v3, v19
	v_cvt_pk_bf16_f32 v8, v8, v10
	ds_write_b16 v7, v8 offset:36688
	ds_write_b16_d16_hi v9, v8 offset:1872
	v_mul_f32_e32 v8, v5, v18
	v_mul_f32_e32 v10, v3, v18
	v_cvt_pk_bf16_f32 v8, v8, v10
	ds_write_b16 v7, v8 offset:36832
	v_mul_f32_e32 v5, v5, v17
	ds_write_b16_d16_hi v9, v8 offset:2016
	v_bfe_u32 v8, v5, 16, 1
	v_add3_u32 v5, v5, v8, s83
	v_mul_f32_e32 v3, v3, v17
	ds_write_b16_d16_hi v7, v5 offset:36976
	v_bfe_u32 v5, v3, 16, 1
	v_add3_u32 v3, v3, v5, s83
	v_mov_b32_e32 v24, 0
	ds_write_b16_d16_hi v9, v3 offset:2160
	v_mov_b32_e32 v25, 0
	v_mov_b32_e32 v20, 0
	v_mov_b32_e32 v21, 0
	v_mov_b32_e32 v18, 0
	v_mov_b32_e32 v19, v24
	v_mov_b32_e32 v16, v24
	v_mov_b32_e32 v17, v24
	v_mov_b32_e32 v14, v24
	v_mov_b32_e32 v15, v24
	v_mov_b32_e32 v12, v24
	v_mov_b32_e32 v13, v24
	v_mov_b32_e32 v10, v24
	v_mov_b32_e32 v11, v24
	v_mov_b32_e32 v8, v24
	v_mov_b32_e32 v9, v24
	v_mov_b32_e32 v22, 0
	v_mov_b32_e32 v23, 0
	s_and_saveexec_b64 s[78:79], s[56:57]
	s_cbranch_execnz .LBB0_305
	s_or_b64 exec, exec, s[78:79]
	s_and_saveexec_b64 s[56:57], s[58:59]
	s_cbranch_execnz .LBB0_306

.LBB0_217:
	s_or_b64 exec, exec, s[54:55]
	v_mul_f32_e32 v7, 0xbfb8aa3b, v14
	v_exp_f32_e32 v7, v7
	v_mul_f32_e32 v1, 0xbfb8aa3b, v20
	v_exp_f32_e32 v1, v1
	v_mul_f32_e32 v5, 0xbfb8aa3b, v16
	v_add_f32_e32 v7, 1.0, v7
	v_rcp_f32_e32 v7, v7
	v_exp_f32_e32 v5, v5
	v_mul_f32_e32 v2, 0xbfb8aa3b, v21
	v_add_f32_e32 v1, 1.0, v1
	v_mul_f32_e32 v7, v14, v7
	v_mul_f32_e32 v14, 0xbfb8aa3b, v15
	v_exp_f32_e32 v14, v14
	v_exp_f32_e32 v2, v2
	v_rcp_f32_e32 v1, v1
	v_mul_f32_e32 v3, 0xbfb8aa3b, v18
	v_add_f32_e32 v14, 1.0, v14
	v_rcp_f32_e32 v14, v14
	v_add_f32_e32 v5, 1.0, v5
	v_exp_f32_e32 v3, v3
	v_rcp_f32_e32 v5, v5
	v_mul_f32_e32 v14, v15, v14
	v_mul_f32_e32 v15, 0xbfb8aa3b, v12
	v_exp_f32_e32 v15, v15
	v_add_f32_e32 v2, 1.0, v2
	v_mul_f32_e32 v1, v20, v1
	v_rcp_f32_e32 v2, v2
	v_add_f32_e32 v15, 1.0, v15
	v_rcp_f32_e32 v15, v15
	v_mul_f32_e32 v4, 0xbfb8aa3b, v19
	v_exp_f32_e32 v4, v4
	v_mul_f32_e32 v1, v26, v1
	v_mul_f32_e32 v12, v12, v15
	v_mul_f32_e32 v15, 0xbfb8aa3b, v13
	v_exp_f32_e32 v15, v15
	v_add_f32_e32 v3, 1.0, v3
	v_mul_f32_e32 v5, v16, v5
	v_bfe_u32 v16, v1, 16, 1
	v_add_f32_e32 v15, 1.0, v15
	v_rcp_f32_e32 v15, v15
	v_rcp_f32_e32 v3, v3
	v_add3_u32 v1, v1, v16, s83
	v_mul_u32_u24_e32 v16, 0x900, v27
	v_mul_f32_e32 v13, v13, v15
	v_mul_f32_e32 v15, 0xbfb8aa3b, v10
	v_exp_f32_e32 v15, v15
	v_mul_f32_e32 v2, v21, v2
	v_add3_u32 v16, 0, v29, v16
	v_add_f32_e32 v4, 1.0, v4
	v_add_f32_e32 v15, 1.0, v15
	v_rcp_f32_e32 v15, v15
	ds_write_b16_d16_hi v16, v1 offset:53248
	v_mul_f32_e32 v1, v26, v2
	v_rcp_f32_e32 v4, v4
	v_mul_f32_e32 v10, v10, v15
	v_mul_f32_e32 v15, 0xbfb8aa3b, v11
	v_exp_f32_e32 v15, v15
	v_mul_f32_e32 v6, 0xbfb8aa3b, v17
	v_mul_f32_e32 v3, v18, v3
	v_exp_f32_e32 v6, v6
	v_add_f32_e32 v15, 1.0, v15
	v_mul_f32_e32 v2, v26, v3
	v_rcp_f32_e32 v15, v15
	v_mul_f32_e32 v4, v19, v4
	v_cvt_pk_bf16_f32 v1, v1, v2
	ds_write_b16 v16, v1 offset:53392
	v_add_f32_e32 v6, 1.0, v6
	ds_write_b16_d16_hi v16, v1 offset:53536
	v_mul_f32_e32 v1, v26, v4
	v_rcp_f32_e32 v6, v6
	v_mul_f32_e32 v11, v11, v15
	v_mul_f32_e32 v15, 0xbfb8aa3b, v8
	v_exp_f32_e32 v15, v15
	v_mul_f32_e32 v2, v26, v5
	v_mul_f32_e32 v6, v17, v6
	v_cvt_pk_bf16_f32 v1, v1, v2
	ds_write_b16 v16, v1 offset:53680
	ds_write_b16_d16_hi v16, v1 offset:53824
	v_mul_f32_e32 v1, v26, v6
	v_add_f32_e32 v15, 1.0, v15
	v_rcp_f32_e32 v15, v15
	v_mul_f32_e32 v2, v26, v7
	v_cvt_pk_bf16_f32 v1, v1, v2
	ds_write_b16 v16, v1 offset:53968
	v_mul_f32_e32 v8, v8, v15
	v_mul_f32_e32 v15, 0xbfb8aa3b, v9
	ds_write_b16_d16_hi v16, v1 offset:54112
	v_mul_f32_e32 v1, v26, v14
	v_exp_f32_e32 v15, v15
	v_mul_f32_e32 v2, v26, v12
	v_add_f32_e32 v15, 1.0, v15
	v_cvt_pk_bf16_f32 v1, v1, v2
	ds_write_b16 v16, v1 offset:54256
	v_rcp_f32_e32 v15, v15
	ds_write_b16_d16_hi v16, v1 offset:54400
	v_mul_f32_e32 v1, v26, v13
	v_mul_f32_e32 v2, v26, v10
	v_mul_f32_e32 v9, v9, v15
	v_mul_f32_e32 v15, 0xbfb8aa3b, v22
	v_exp_f32_e32 v15, v15
	v_cvt_pk_bf16_f32 v1, v1, v2
	ds_write_b16 v16, v1 offset:54544
	v_mul_f32_e32 v0, 0xbfb8aa3b, v23
	ds_write_b16_d16_hi v16, v1 offset:54688
	v_mul_f32_e32 v1, v26, v11
	v_exp_f32_e32 v0, v0
	v_add_f32_e32 v15, 1.0, v15
	v_mul_f32_e32 v2, v26, v8
	v_rcp_f32_e32 v15, v15
	v_add_f32_e32 v0, 1.0, v0
	v_cvt_pk_bf16_f32 v1, v1, v2
	ds_write_b16 v16, v1 offset:54832
	v_rcp_f32_e32 v0, v0
	ds_write_b16_d16_hi v16, v1 offset:54976
	v_mul_f32_e32 v1, v26, v9
	v_mul_f32_e32 v15, v22, v15
	v_mul_f32_e32 v2, v26, v15
	v_mul_f32_e32 v0, v23, v0
	v_cvt_pk_bf16_f32 v1, v1, v2
	ds_write_b16 v16, v1 offset:55120
	v_mul_f32_e32 v0, v26, v0
	ds_write_b16_d16_hi v16, v1 offset:55264
	v_bfe_u32 v1, v0, 16, 1
	v_add3_u32 v0, v0, v1, s83
	ds_write_b16_d16_hi v16, v0 offset:55408
	v_and_b32_e32 v42, 31, v36
	s_cmp_lt_u32 s31, 3
	s_cbranch_scc0 .Lp3_pf_skip
	v_ashrrev_i32_e32 v244, 3, v35
	s_add_i32 s98, s12, s28
	v_add_u32_e32 v244, s98, v244
	v_and_b32_e32 v246, 7, v35
	v_lshlrev_b32_e32 v246, 5, v246
	s_lshl_b32 s98, s31, 8
	s_addk_i32 s98, 0x100
	v_or_b32_e32 v246, s98, v246
	v_mov_b32_e32 v247, 0
	v_lshl_add_u64 v[246:247], s[62:63], 0, v[246:247]
	v_mad_u64_u32 v[240:241], s[98:99], v244, s91, v[246:247]
	v_mov_b32_e32 v244, 0xffffe800
	v_add_co_u32_e64 v242, s[98:99], v240, v244
	s_nop 1
	v_addc_co_u32_e64 v243, s[98:99], v241, -1, s[98:99]
	global_load_dwordx4 v[192:195], v[240:241], off
	global_load_dwordx4 v[212:215], v[240:241], off offset:16
	global_load_dwordx4 v[168:171], v[240:241], off offset:-3072
	global_load_dwordx4 v[172:175], v[240:241], off offset:-3056
	global_load_dwordx4 v[140:143], v[242:243], off
	global_load_dwordx4 v[144:147], v[242:243], off offset:16
	global_load_dwordx4 v[116:119], v[242:243], off offset:-3072
	global_load_dwordx4 v[120:123], v[242:243], off offset:-3056
	global_load_dwordx4 v[216:219], v[240:241], off offset:1024
	global_load_dwordx4 v[220:223], v[240:241], off offset:1040
	global_load_dwordx4 v[176:179], v[240:241], off offset:-2048
	global_load_dwordx4 v[180:183], v[240:241], off offset:-2032
	global_load_dwordx4 v[148:151], v[242:243], off offset:1024
	global_load_dwordx4 v[152:155], v[242:243], off offset:1040
	global_load_dwordx4 v[124:127], v[242:243], off offset:-2048
	global_load_dwordx4 v[128:131], v[242:243], off offset:-2032
	global_load_dwordx4 v[232:235], v[240:241], off offset:2048
	global_load_dwordx4 v[236:239], v[240:241], off offset:2064
	global_load_dwordx4 v[184:187], v[240:241], off offset:-1024
	global_load_dwordx4 v[188:191], v[240:241], off offset:-1008
	global_load_dwordx4 v[156:159], v[242:243], off offset:2048
	global_load_dwordx4 v[164:167], v[242:243], off offset:2064
	global_load_dwordx4 v[132:135], v[242:243], off offset:-1024
	global_load_dwordx4 v[136:139], v[242:243], off offset:-1008

.LBB0_290:
	v_and_b32_e32 v44, 63, v36
	v_mov_b32_e32 v0, 0
	s_andn2_b64 vcc, exec, s[54:55]
	v_lshlrev_b32_e32 v45, 1, v42
	v_mov_b32_e32 v1, 0
	v_mov_b32_e32 v2, 0
	v_mov_b32_e32 v3, 0
	v_mov_b32_e32 v4, 0
	v_mov_b32_e32 v5, 0
	v_mov_b32_e32 v6, 0
	v_mov_b32_e32 v7, 0
	v_mov_b32_e32 v8, 0
	v_mov_b32_e32 v9, 0
	v_mov_b32_e32 v10, 0
	v_mov_b32_e32 v11, 0
	v_mov_b32_e32 v12, 0
	v_mov_b32_e32 v13, 0
	v_mov_b32_e32 v14, 0
	v_mov_b32_e32 v15, 0
	s_cbranch_vccnz .LBB0_293
	v_lshl_add_u32 v0, v42, 2, s20
	v_mov_b32_e32 v1, s21
	v_add_u32_e32 v2, 0x200, v0
	ds_read2_b32 v[22:23], v2 offset0:76 offset1:144
	v_add_u32_e32 v2, 0x400, v0
	ds_read2_b32 v[30:31], v2 offset0:84 offset1:152
	v_add_u32_e32 v2, 0x600, v0
	ds_read2_b32 v[90:91], v2 offset0:92 offset1:160
	v_add_u32_e32 v2, 0x800, v0
	ds_read2_b32 v[92:93], v2 offset0:100 offset1:168
	v_add_u32_e32 v2, 0xa00, v0
	ds_read2_b32 v[94:95], v2 offset0:108 offset1:176
	v_add_u32_e32 v2, 0xc00, v0
	ds_read2_b32 v[96:97], v2 offset0:116 offset1:184
	v_add_u32_e32 v2, 0xe00, v0
	ds_read2_b32 v[98:99], v2 offset0:124 offset1:192
	v_add_u32_e32 v2, 0x1000, v0
	ds_read2_b32 v[100:101], v2 offset0:132 offset1:200
	v_add_u32_e32 v2, 0x1400, v0
	ds_read2_b32 v[14:15], v0 offset0:68 offset1:136
	ds_read2_b32 v[102:103], v2 offset0:12 offset1:80
	ds_read2_b32 v[104:105], v2 offset0:148 offset1:216
	v_add_u32_e32 v2, 0x1800, v0
	ds_read2_b32 v[106:107], v2 offset0:28 offset1:96
	ds_read2_b32 v[108:109], v2 offset0:164 offset1:232
	v_add_u32_e32 v2, 0x1c00, v0
	ds_read2_b32 v[110:111], v2 offset0:44 offset1:112
	ds_read2_b32 v[112:113], v2 offset0:180 offset1:248
	ds_read_b32 v25, v0 offset:8432
	ds_read_b128 v[2:5], v1 offset:272
	ds_read_b128 v[6:9], v1 offset:288
	ds_read_b128 v[10:13], v1 offset:304
	ds_read_b128 v[18:21], v1 offset:320
	ds_read_b128 v[26:29], v1 offset:336
	ds_read_b128 v[46:49], v1 offset:352
	ds_read_b128 v[50:53], v1 offset:368
	ds_read_b128 v[54:57], v1 offset:384
	ds_read_b128 v[58:61], v1 offset:544
	ds_read_b128 v[62:65], v1 offset:560
	ds_read_b128 v[66:69], v1 offset:576
	ds_read_b128 v[70:73], v1 offset:592
	ds_read_b128 v[74:77], v1 offset:608
	ds_read_b128 v[78:81], v1 offset:624
	ds_read_b128 v[82:85], v1 offset:640
	ds_read_b128 v[86:89], v1 offset:656
	v_or_b32_e32 v0, s37, v42
	v_mul_lo_u32 v0, v0, s95
	v_add3_u32 v0, s22, v0, v45
	s_waitcnt lgkmcnt(14)
	v_xor_b32_e32 v17, 0x80000000, v14
	v_fma_f32 v16, v14, v4, -v15
	v_fma_f32 v15, v14, v5, -v22
	s_waitcnt lgkmcnt(7)
	v_fma_f32 v58, v14, v6, -v23
	v_fma_f32 v30, v14, v7, -v30
	v_fma_f32 v31, v14, v8, -v31
	v_fma_f32 v59, v14, v9, -v90
	v_fma_f32 v60, v14, v10, -v91
	v_fma_f32 v90, v14, v11, -v92
	v_fma_f32 v91, v14, v12, -v93
	v_fma_f32 v92, v14, v13, -v94
	v_fma_f32 v93, v14, v18, -v95
	v_fma_f32 v19, v14, v19, -v96
	v_fma_f32 v94, v14, v20, -v97
	v_fma_f32 v95, v14, v21, -v98
	v_fma_f32 v96, v14, v26, -v99
	v_fma_f32 v97, v14, v27, -v100
	v_fma_f32 v98, v14, v28, -v101
	v_fma_f32 v99, v14, v29, -v102
	v_fma_f32 v100, v14, v46, -v103
	v_fma_f32 v101, v14, v47, -v104
	v_fma_f32 v102, v14, v48, -v105
	v_fma_f32 v103, v14, v49, -v106
	v_fma_f32 v104, v14, v50, -v107
	v_fma_f32 v105, v14, v51, -v108
	v_fma_f32 v106, v14, v52, -v109
	v_fma_f32 v107, v14, v53, -v110
	v_fma_f32 v54, v14, v54, -v111
	v_fma_f32 v55, v14, v55, -v112
	v_fma_f32 v56, v14, v56, -v113
	v_fma_f32 v14, v14, v57, -v25
	ds_read_b128 v[2:5], v1 offset:832
	ds_read_b128 v[6:9], v1 offset:848
	ds_read_b128 v[10:13], v1 offset:864
	ds_read_b128 v[20:23], v1 offset:880
	ds_read_b128 v[26:29], v1 offset:896
	ds_read_b128 v[46:49], v1 offset:912
	ds_read_b128 v[50:53], v1 offset:928
	v_fma_f32 v18, -v16, v61, v15
	s_waitcnt lgkmcnt(13)
	v_fma_f32 v15, -v16, v62, v58
	v_fma_f32 v25, -v16, v63, v30
	v_fma_f32 v30, -v16, v64, v31
	v_fma_f32 v31, -v16, v65, v59
	s_waitcnt lgkmcnt(7)
	v_fma_f32 v14, -v16, v89, v14
	v_fma_f32 v108, -v16, v66, v60
	v_fma_f32 v90, -v16, v67, v90
	v_fma_f32 v91, -v16, v68, v91
	v_fma_f32 v92, -v16, v69, v92
	v_fma_f32 v93, -v16, v70, v93
	v_fma_f32 v109, -v16, v71, v19
	v_fma_f32 v94, -v16, v72, v94
	v_fma_f32 v95, -v16, v73, v95
	v_fma_f32 v96, -v16, v74, v96
	v_fma_f32 v97, -v16, v75, v97
	v_fma_f32 v98, -v16, v76, v98
	v_fma_f32 v99, -v16, v77, v99
	v_fma_f32 v100, -v16, v78, v100
	v_fma_f32 v101, -v16, v79, v101
	v_fma_f32 v102, -v16, v80, v102
	v_fma_f32 v103, -v16, v81, v103
	v_fma_f32 v82, -v16, v82, v104
	v_fma_f32 v83, -v16, v83, v105
	v_fma_f32 v84, -v16, v84, v106
	v_fma_f32 v85, -v16, v85, v107
	v_fma_f32 v86, -v16, v86, v54
	v_fma_f32 v87, -v16, v87, v55
	v_fma_f32 v88, -v16, v88, v56
	ds_read_b128 v[54:57], v1 offset:1104
	ds_read_b128 v[58:61], v1 offset:1120
	ds_read_b128 v[62:65], v1 offset:1136
	ds_read_b128 v[66:69], v1 offset:1152
	ds_read_b128 v[70:73], v1 offset:1168
	ds_read_b128 v[74:77], v1 offset:1184
	ds_read_b128 v[78:81], v1 offset:1200
	s_waitcnt lgkmcnt(13)
	v_fma_f32 v19, -v18, v2, v15
	v_fma_f32 v15, -v18, v3, v25
	v_fma_f32 v25, -v18, v4, v30
	v_fma_f32 v30, -v18, v5, v31
	s_waitcnt lgkmcnt(12)
	v_fma_f32 v31, -v18, v6, v108
	s_waitcnt lgkmcnt(6)
	v_fma_f32 v54, -v18, v7, v90
	v_fma_f32 v21, -v18, v21, v97
	v_fma_f32 v22, -v18, v22, v98
	v_fma_f32 v23, -v18, v23, v99
	v_fma_f32 v14, -v18, v53, v14
	v_fma_f32 v89, -v18, v8, v91
	v_fma_f32 v90, -v18, v9, v92
	v_fma_f32 v91, -v18, v10, v93
	v_fma_f32 v92, -v18, v11, v109
	v_fma_f32 v93, -v18, v12, v94
	v_fma_f32 v94, -v18, v13, v95
	v_fma_f32 v95, -v18, v20, v96
	v_fma_f32 v96, -v18, v26, v100
	v_fma_f32 v97, -v18, v27, v101
	v_fma_f32 v98, -v18, v28, v102
	v_fma_f32 v99, -v18, v29, v103
	v_fma_f32 v100, -v18, v46, v82
	v_fma_f32 v101, -v18, v47, v83
	v_fma_f32 v102, -v18, v48, v84
	v_fma_f32 v103, -v18, v49, v85
	v_fma_f32 v86, -v18, v50, v86
	v_fma_f32 v87, -v18, v51, v87
	v_fma_f32 v88, -v18, v52, v88
	ds_read_b128 v[2:5], v1 offset:1376
	ds_read_b128 v[6:9], v1 offset:1392
	ds_read_b128 v[10:13], v1 offset:1408
	ds_read_b128 v[26:29], v1 offset:1424
	ds_read_b128 v[46:49], v1 offset:1440
	ds_read_b128 v[50:53], v1 offset:1456
	ds_read_b128 v[82:85], v1 offset:1472
	v_fma_f32 v20, -v19, v55, v15
	s_waitcnt lgkmcnt(6)
	v_fma_f32 v2, -v19, v56, v25
	v_fma_f32 v3, -v19, v57, v30
	v_fma_f32 v15, -v19, v58, v31
	v_fma_f32 v25, -v19, v59, v54
	v_fma_f32 v30, -v19, v60, v89
	v_fma_f32 v31, -v19, v61, v90
	v_fma_f32 v22, -v19, v68, v22
	v_fma_f32 v23, -v19, v69, v23
	v_fma_f32 v14, -v19, v81, v14
	v_fma_f32 v89, -v19, v62, v91
	v_fma_f32 v90, -v19, v63, v92
	v_fma_f32 v91, -v19, v64, v93
	v_fma_f32 v92, -v19, v65, v94
	v_fma_f32 v93, -v19, v66, v95
	v_fma_f32 v94, -v19, v67, v21
	v_fma_f32 v95, -v19, v70, v96
	v_fma_f32 v96, -v19, v71, v97
	v_fma_f32 v97, -v19, v72, v98
	v_fma_f32 v98, -v19, v73, v99
	v_fma_f32 v99, -v19, v74, v100
	v_fma_f32 v100, -v19, v75, v101
	v_fma_f32 v101, -v19, v76, v102
	v_fma_f32 v102, -v19, v77, v103
	v_fma_f32 v86, -v19, v78, v86
	v_fma_f32 v87, -v19, v79, v87
	v_fma_f32 v88, -v19, v80, v88
	ds_read_b128 v[54:57], v1 offset:1648
	ds_read_b128 v[58:61], v1 offset:1664
	ds_read_b128 v[62:65], v1 offset:1680
	ds_read_b128 v[66:69], v1 offset:1696
	ds_read_b128 v[70:73], v1 offset:1712
	ds_read_b128 v[74:77], v1 offset:1728
	ds_read_b128 v[78:81], v1 offset:1744
	v_fma_f32 v21, -v20, v4, v2
	s_waitcnt lgkmcnt(6)
	v_fma_f32 v54, -v20, v5, v3
	v_fma_f32 v15, -v20, v6, v15
	v_fma_f32 v25, -v20, v7, v25
	v_fma_f32 v30, -v20, v8, v30
	v_fma_f32 v31, -v20, v9, v31
	v_fma_f32 v55, -v20, v10, v89
	v_fma_f32 v56, -v20, v11, v90
	v_fma_f32 v23, -v20, v29, v23
	v_fma_f32 v14, -v20, v85, v14
	v_fma_f32 v89, -v20, v12, v91
	v_fma_f32 v90, -v20, v13, v92
	v_fma_f32 v91, -v20, v26, v93
	v_fma_f32 v92, -v20, v27, v94
	v_fma_f32 v93, -v20, v28, v22
	v_fma_f32 v94, -v20, v46, v95
	v_fma_f32 v95, -v20, v47, v96
	v_fma_f32 v96, -v20, v48, v97
	v_fma_f32 v97, -v20, v49, v98
	v_fma_f32 v98, -v20, v50, v99
	v_fma_f32 v99, -v20, v51, v100
	v_fma_f32 v100, -v20, v52, v101
	v_fma_f32 v101, -v20, v53, v102
	v_fma_f32 v82, -v20, v82, v86
	v_fma_f32 v83, -v20, v83, v87
	v_fma_f32 v84, -v20, v84, v88
	ds_read_b128 v[2:5], v1 offset:1936
	ds_read_b128 v[6:9], v1 offset:1952
	ds_read_b128 v[10:13], v1 offset:1968
	ds_read_b128 v[26:29], v1 offset:1984
	ds_read_b128 v[46:49], v1 offset:2000
	ds_read_b128 v[50:53], v1 offset:2016
	v_fma_f32 v22, -v21, v57, v54
	s_waitcnt lgkmcnt(11)
	v_fma_f32 v15, -v21, v58, v15
	v_fma_f32 v25, -v21, v59, v25
	v_fma_f32 v30, -v21, v60, v30
	v_fma_f32 v31, -v21, v61, v31
	s_waitcnt lgkmcnt(6)
	v_fma_f32 v14, -v21, v81, v14
	v_fma_f32 v85, -v21, v62, v55
	v_fma_f32 v86, -v21, v63, v56
	v_fma_f32 v87, -v21, v64, v89
	v_fma_f32 v88, -v21, v65, v90
	v_fma_f32 v89, -v21, v66, v91
	v_fma_f32 v90, -v21, v67, v92
	v_fma_f32 v91, -v21, v68, v93
	v_fma_f32 v92, -v21, v69, v23
	v_fma_f32 v93, -v21, v70, v94
	v_fma_f32 v94, -v21, v71, v95
	v_fma_f32 v95, -v21, v72, v96
	v_fma_f32 v96, -v21, v73, v97
	v_fma_f32 v97, -v21, v74, v98
	v_fma_f32 v98, -v21, v75, v99
	v_fma_f32 v99, -v21, v76, v100
	v_fma_f32 v100, -v21, v77, v101
	v_fma_f32 v78, -v21, v78, v82
	v_fma_f32 v79, -v21, v79, v83
	v_fma_f32 v80, -v21, v80, v84
	ds_read_b128 v[54:57], v1 offset:2208
	ds_read_b128 v[58:61], v1 offset:2224
	ds_read_b128 v[62:65], v1 offset:2240
	ds_read_b128 v[66:69], v1 offset:2256
	ds_read_b128 v[70:73], v1 offset:2272
	ds_read_b128 v[74:77], v1 offset:2288
	s_waitcnt lgkmcnt(11)
	v_fma_f32 v23, -v22, v2, v15
	v_fma_f32 v15, -v22, v3, v25
	s_waitcnt lgkmcnt(5)
	v_fma_f32 v54, -v22, v4, v30
	v_fma_f32 v26, -v22, v26, v93
	v_fma_f32 v27, -v22, v27, v94
	v_fma_f32 v14, -v22, v53, v14
	v_fma_f32 v81, -v22, v5, v31
	v_fma_f32 v82, -v22, v6, v85
	v_fma_f32 v83, -v22, v7, v86
	v_fma_f32 v84, -v22, v8, v87
	v_fma_f32 v85, -v22, v9, v88
	v_fma_f32 v86, -v22, v10, v89
	v_fma_f32 v87, -v22, v11, v90
	v_fma_f32 v88, -v22, v12, v91
	v_fma_f32 v89, -v22, v13, v92
	v_fma_f32 v90, -v22, v28, v95
	v_fma_f32 v91, -v22, v29, v96
	v_fma_f32 v92, -v22, v46, v97
	v_fma_f32 v93, -v22, v47, v98
	v_fma_f32 v94, -v22, v48, v99
	v_fma_f32 v95, -v22, v49, v100
	v_fma_f32 v78, -v22, v50, v78
	v_fma_f32 v79, -v22, v51, v79
	v_fma_f32 v80, -v22, v52, v80
	ds_read_b128 v[2:5], v1 offset:2480
	ds_read_b128 v[6:9], v1 offset:2496
	ds_read_b128 v[10:13], v1 offset:2512
	ds_read_b128 v[28:31], v1 offset:2528
	ds_read_b128 v[46:49], v1 offset:2544
	ds_read_b128 v[50:53], v1 offset:2560
	v_fma_f32 v25, -v23, v55, v15
	s_waitcnt lgkmcnt(5)
	v_fma_f32 v2, -v23, v56, v54
	v_fma_f32 v3, -v23, v57, v81
	v_fma_f32 v15, -v23, v58, v82
	v_fma_f32 v27, -v23, v67, v27
	v_fma_f32 v14, -v23, v77, v14
	v_fma_f32 v81, -v23, v59, v83
	v_fma_f32 v82, -v23, v60, v84
	v_fma_f32 v83, -v23, v61, v85
	v_fma_f32 v84, -v23, v62, v86
	v_fma_f32 v85, -v23, v63, v87
	v_fma_f32 v86, -v23, v64, v88
	v_fma_f32 v87, -v23, v65, v89
	v_fma_f32 v88, -v23, v66, v26
	v_fma_f32 v89, -v23, v68, v90
	v_fma_f32 v90, -v23, v69, v91
	v_fma_f32 v91, -v23, v70, v92
	v_fma_f32 v92, -v23, v71, v93
	v_fma_f32 v93, -v23, v72, v94
	v_fma_f32 v94, -v23, v73, v95
	v_fma_f32 v78, -v23, v74, v78
	v_fma_f32 v79, -v23, v75, v79
	v_fma_f32 v80, -v23, v76, v80
	ds_read_b128 v[54:57], v1 offset:2752
	ds_read_b128 v[58:61], v1 offset:2768
	ds_read_b128 v[62:65], v1 offset:2784
	ds_read_b128 v[66:69], v1 offset:2800
	ds_read_b128 v[70:73], v1 offset:2816
	ds_read_b128 v[74:77], v1 offset:2832
	v_fma_f32 v26, -v25, v4, v2
	s_waitcnt lgkmcnt(5)
	v_fma_f32 v54, -v25, v5, v3
	v_fma_f32 v15, -v25, v6, v15
	v_fma_f32 v55, -v25, v7, v81
	v_fma_f32 v56, -v25, v8, v82
	v_fma_f32 v28, -v25, v28, v88
	v_fma_f32 v29, -v25, v29, v27
	v_fma_f32 v30, -v25, v30, v89
	v_fma_f32 v31, -v25, v31, v90
	v_fma_f32 v14, -v25, v53, v14
	v_fma_f32 v81, -v25, v9, v83
	v_fma_f32 v82, -v25, v10, v84
	v_fma_f32 v83, -v25, v11, v85
	v_fma_f32 v84, -v25, v12, v86
	v_fma_f32 v85, -v25, v13, v87
	v_fma_f32 v86, -v25, v46, v91
	v_fma_f32 v87, -v25, v47, v92
	v_fma_f32 v88, -v25, v48, v93
	v_fma_f32 v89, -v25, v49, v94
	v_fma_f32 v78, -v25, v50, v78
	v_fma_f32 v79, -v25, v51, v79
	v_fma_f32 v80, -v25, v52, v80
	ds_read_b128 v[2:5], v1 offset:3040
	ds_read_b128 v[6:9], v1 offset:3056
	ds_read_b128 v[10:13], v1 offset:3072
	ds_read_b128 v[46:49], v1 offset:3088
	ds_read_b128 v[50:53], v1 offset:3104
	v_fma_f32 v27, -v26, v57, v54
	s_waitcnt lgkmcnt(9)
	v_fma_f32 v15, -v26, v58, v15
	s_waitcnt lgkmcnt(5)
	v_fma_f32 v14, -v26, v77, v14
	v_fma_f32 v90, -v26, v59, v55
	v_fma_f32 v91, -v26, v60, v56
	v_fma_f32 v81, -v26, v61, v81
	v_fma_f32 v82, -v26, v62, v82
	v_fma_f32 v83, -v26, v63, v83
	v_fma_f32 v84, -v26, v64, v84
	v_fma_f32 v85, -v26, v65, v85
	v_fma_f32 v92, -v26, v66, v28
	v_fma_f32 v93, -v26, v67, v29
	v_fma_f32 v94, -v26, v68, v30
	v_fma_f32 v95, -v26, v69, v31
	v_fma_f32 v70, -v26, v70, v86
	v_fma_f32 v71, -v26, v71, v87
	v_fma_f32 v72, -v26, v72, v88
	v_fma_f32 v73, -v26, v73, v89
	v_fma_f32 v74, -v26, v74, v78
	v_fma_f32 v75, -v26, v75, v79
	v_fma_f32 v76, -v26, v76, v80
	ds_read_b128 v[28:31], v1 offset:3312
	ds_read_b128 v[54:57], v1 offset:3328
	ds_read_b128 v[58:61], v1 offset:3344
	ds_read_b128 v[62:65], v1 offset:3360
	ds_read_b128 v[66:69], v1 offset:3376
	s_waitcnt lgkmcnt(4)
	v_fma_f32 v28, -v27, v2, v15
	v_fma_f32 v15, -v27, v3, v90
	v_fma_f32 v14, -v27, v53, v14
	v_fma_f32 v77, -v27, v4, v91
	v_fma_f32 v78, -v27, v5, v81
	v_fma_f32 v79, -v27, v6, v82
	v_fma_f32 v80, -v27, v7, v83
	v_fma_f32 v81, -v27, v8, v84
	v_fma_f32 v82, -v27, v9, v85
	v_fma_f32 v83, -v27, v10, v92
	v_fma_f32 v84, -v27, v11, v93
	v_fma_f32 v85, -v27, v12, v94
	v_fma_f32 v86, -v27, v13, v95
	v_fma_f32 v70, -v27, v46, v70
	v_fma_f32 v71, -v27, v47, v71
	v_fma_f32 v72, -v27, v48, v72
	v_fma_f32 v73, -v27, v49, v73
	v_fma_f32 v74, -v27, v50, v74
	v_fma_f32 v75, -v27, v51, v75
	v_fma_f32 v76, -v27, v52, v76
	ds_read_b128 v[2:5], v1 offset:3584
	ds_read_b128 v[6:9], v1 offset:3600
	ds_read_b128 v[10:13], v1 offset:3616
	ds_read_b128 v[46:49], v1 offset:3632
	ds_read_b128 v[50:53], v1 offset:3648
	v_fma_f32 v29, -v28, v29, v15
	s_waitcnt lgkmcnt(4)
	v_fma_f32 v2, -v28, v30, v77
	v_fma_f32 v3, -v28, v31, v78
	v_fma_f32 v15, -v28, v54, v79
	v_fma_f32 v30, -v28, v55, v80
	v_fma_f32 v14, -v28, v69, v14
	v_fma_f32 v77, -v28, v56, v81
	v_fma_f32 v78, -v28, v57, v82
	v_fma_f32 v79, -v28, v58, v83
	v_fma_f32 v80, -v28, v59, v84
	v_fma_f32 v81, -v28, v60, v85
	v_fma_f32 v82, -v28, v61, v86
	v_fma_f32 v83, -v28, v62, v70
	v_fma_f32 v84, -v28, v63, v71
	v_fma_f32 v85, -v28, v64, v72
	v_fma_f32 v86, -v28, v65, v73
	v_fma_f32 v74, -v28, v66, v74
	v_fma_f32 v75, -v28, v67, v75
	v_fma_f32 v76, -v28, v68, v76
	ds_read_b128 v[54:57], v1 offset:3856
	ds_read_b128 v[58:61], v1 offset:3872
	ds_read_b128 v[62:65], v1 offset:3888
	ds_read_b128 v[66:69], v1 offset:3904
	ds_read_b128 v[70:73], v1 offset:3920
	v_fma_f32 v31, -v29, v4, v2
	s_waitcnt lgkmcnt(4)
	v_fma_f32 v54, -v29, v5, v3
	v_fma_f32 v15, -v29, v6, v15
	v_fma_f32 v30, -v29, v7, v30
	v_fma_f32 v55, -v29, v8, v77
	v_fma_f32 v56, -v29, v9, v78
	v_fma_f32 v46, -v29, v46, v83
	v_fma_f32 v52, -v29, v52, v76
	v_fma_f32 v14, -v29, v53, v14
	v_fma_f32 v77, -v29, v10, v79
	v_fma_f32 v78, -v29, v11, v80
	v_fma_f32 v79, -v29, v12, v81
	v_fma_f32 v80, -v29, v13, v82
	v_fma_f32 v81, -v29, v47, v84
	v_fma_f32 v82, -v29, v48, v85
	v_fma_f32 v83, -v29, v49, v86
	v_fma_f32 v74, -v29, v50, v74
	v_fma_f32 v75, -v29, v51, v75
	ds_read_b128 v[2:5], v1 offset:4144
	ds_read_b128 v[6:9], v1 offset:4160
	ds_read_b128 v[10:13], v1 offset:4176
	ds_read_b128 v[48:51], v1 offset:4192
	v_fma_f32 v47, -v31, v57, v54
	s_waitcnt lgkmcnt(7)
	v_fma_f32 v15, -v31, v58, v15
	s_waitcnt lgkmcnt(5)
	v_fma_f32 v46, -v31, v66, v46
	s_waitcnt lgkmcnt(4)
	v_fma_f32 v14, -v31, v73, v14
	v_fma_f32 v76, -v31, v59, v30
	v_fma_f32 v84, -v31, v60, v55
	v_fma_f32 v85, -v31, v61, v56
	v_fma_f32 v77, -v31, v62, v77
	v_fma_f32 v78, -v31, v63, v78
	v_fma_f32 v79, -v31, v64, v79
	v_fma_f32 v80, -v31, v65, v80
	v_fma_f32 v81, -v31, v67, v81
	v_fma_f32 v68, -v31, v68, v82
	v_fma_f32 v69, -v31, v69, v83
	v_fma_f32 v70, -v31, v70, v74
	v_fma_f32 v71, -v31, v71, v75
	v_fma_f32 v72, -v31, v72, v52
	ds_read_b128 v[52:55], v1 offset:4416
	ds_read_b128 v[56:59], v1 offset:4432
	ds_read_b128 v[60:63], v1 offset:4448
	ds_read_b128 v[64:67], v1 offset:4464
	s_waitcnt lgkmcnt(7)
	v_fma_f32 v30, -v47, v2, v15
	v_fma_f32 v15, -v47, v3, v76
	s_waitcnt lgkmcnt(3)
	v_fma_f32 v52, -v47, v4, v84
	v_fma_f32 v48, -v47, v48, v70
	v_fma_f32 v49, -v47, v49, v71
	v_fma_f32 v50, -v47, v50, v72
	v_fma_f32 v14, -v47, v51, v14
	v_fma_f32 v73, -v47, v5, v85
	v_fma_f32 v74, -v47, v6, v77
	v_fma_f32 v75, -v47, v7, v78
	v_fma_f32 v76, -v47, v8, v79
	v_fma_f32 v77, -v47, v9, v80
	v_fma_f32 v78, -v47, v10, v46
	v_fma_f32 v79, -v47, v11, v81
	v_fma_f32 v80, -v47, v12, v68
	v_fma_f32 v81, -v47, v13, v69
	ds_read_b128 v[2:5], v1 offset:4688
	ds_read_b128 v[6:9], v1 offset:4704
	ds_read_b128 v[10:13], v1 offset:4720
	ds_read_b128 v[68:71], v1 offset:4736
	v_fma_f32 v46, -v30, v53, v15
	s_waitcnt lgkmcnt(3)
	v_fma_f32 v2, -v30, v54, v52
	v_fma_f32 v3, -v30, v55, v73
	v_fma_f32 v15, -v30, v56, v74
	v_fma_f32 v14, -v30, v67, v14
	v_fma_f32 v72, -v30, v57, v75
	v_fma_f32 v73, -v30, v58, v76
	v_fma_f32 v74, -v30, v59, v77
	v_fma_f32 v75, -v30, v60, v78
	v_fma_f32 v76, -v30, v61, v79
	v_fma_f32 v77, -v30, v62, v80
	v_fma_f32 v78, -v30, v63, v81
	v_fma_f32 v64, -v30, v64, v48
	v_fma_f32 v65, -v30, v65, v49
	v_fma_f32 v66, -v30, v66, v50
	ds_read_b128 v[48:51], v1 offset:4960
	ds_read_b128 v[52:55], v1 offset:4976
	ds_read_b128 v[56:59], v1 offset:4992
	ds_read_b128 v[60:63], v1 offset:5008
	s_waitcnt lgkmcnt(3)
	v_fma_f32 v48, -v46, v4, v2
	v_fma_f32 v49, -v46, v5, v3
	v_fma_f32 v15, -v46, v6, v15
	v_fma_f32 v50, -v46, v7, v72
	v_fma_f32 v14, -v46, v71, v14
	v_fma_f32 v67, -v46, v8, v73
	v_fma_f32 v72, -v46, v9, v74
	v_fma_f32 v73, -v46, v10, v75
	v_fma_f32 v74, -v46, v11, v76
	v_fma_f32 v75, -v46, v12, v77
	v_fma_f32 v76, -v46, v13, v78
	v_fma_f32 v64, -v46, v68, v64
	v_fma_f32 v65, -v46, v69, v65
	v_fma_f32 v66, -v46, v70, v66
	ds_read_b128 v[2:5], v1 offset:5248
	ds_read_b128 v[6:9], v1 offset:5264
	ds_read_b128 v[10:13], v1 offset:5280
	v_fma_f32 v49, -v48, v51, v49
	s_waitcnt lgkmcnt(5)
	v_fma_f32 v15, -v48, v52, v15
	s_waitcnt lgkmcnt(3)
	v_fma_f32 v14, -v48, v63, v14
	v_fma_f32 v68, -v48, v53, v50
	v_fma_f32 v67, -v48, v54, v67
	v_fma_f32 v69, -v48, v55, v72
	v_fma_f32 v70, -v48, v56, v73
	v_fma_f32 v71, -v48, v57, v74
	v_fma_f32 v72, -v48, v58, v75
	v_fma_f32 v73, -v48, v59, v76
	v_fma_f32 v64, -v48, v60, v64
	v_fma_f32 v65, -v48, v61, v65
	v_fma_f32 v62, -v48, v62, v66
	ds_read_b128 v[50:53], v1 offset:5520
	ds_read_b128 v[54:57], v1 offset:5536
	ds_read_b128 v[58:61], v1 offset:5552
	s_waitcnt lgkmcnt(2)
	v_fma_f32 v50, -v49, v2, v15
	v_fma_f32 v15, -v49, v3, v68
	v_fma_f32 v14, -v49, v13, v14
	v_fma_f32 v63, -v49, v4, v67
	v_fma_f32 v66, -v49, v5, v69
	v_fma_f32 v67, -v49, v6, v70
	v_fma_f32 v68, -v49, v7, v71
	v_fma_f32 v69, -v49, v8, v72
	v_fma_f32 v70, -v49, v9, v73
	v_fma_f32 v64, -v49, v10, v64
	v_fma_f32 v65, -v49, v11, v65
	v_fma_f32 v62, -v49, v12, v62
	ds_read_b128 v[2:5], v1 offset:5792
	ds_read_b128 v[6:9], v1 offset:5808
	ds_read_b128 v[10:13], v1 offset:5824
	v_fma_f32 v51, -v50, v51, v15
	s_waitcnt lgkmcnt(2)
	v_fma_f32 v2, -v50, v52, v63
	v_fma_f32 v3, -v50, v53, v66
	v_fma_f32 v15, -v50, v54, v67
	v_fma_f32 v14, -v50, v61, v14
	v_fma_f32 v66, -v50, v55, v68
	v_fma_f32 v67, -v50, v56, v69
	v_fma_f32 v68, -v50, v57, v70
	v_fma_f32 v64, -v50, v58, v64
	v_fma_f32 v65, -v50, v59, v65
	v_fma_f32 v69, -v50, v60, v62
	ds_read_b128 v[52:55], v1 offset:6064
	ds_read_b128 v[56:59], v1 offset:6080
	ds_read_b128 v[60:63], v1 offset:6096
	s_waitcnt lgkmcnt(2)
	v_fma_f32 v52, -v51, v4, v2
	v_fma_f32 v53, -v51, v5, v3
	v_fma_f32 v15, -v51, v6, v15
	v_fma_f32 v54, -v51, v7, v66
	v_fma_f32 v10, -v51, v10, v64
	v_fma_f32 v11, -v51, v11, v65
	v_fma_f32 v12, -v51, v12, v69
	v_fma_f32 v13, -v51, v13, v14
	v_fma_f32 v66, -v51, v8, v67
	v_fma_f32 v67, -v51, v9, v68
	ds_read_b128 v[2:5], v1 offset:6352
	ds_read_b128 v[6:9], v1 offset:6368
	v_fma_f32 v53, -v52, v55, v53
	s_waitcnt lgkmcnt(3)
	v_fma_f32 v14, -v52, v56, v15
	v_fma_f32 v15, -v52, v57, v54
	v_fma_f32 v54, -v52, v58, v66
	v_fma_f32 v55, -v52, v59, v67
	s_waitcnt lgkmcnt(2)
	v_fma_f32 v56, -v52, v60, v10
	v_fma_f32 v58, -v52, v61, v11
	v_fma_f32 v59, -v52, v62, v12
	v_fma_f32 v64, -v52, v63, v13
	ds_read_b128 v[10:13], v1 offset:6624
	ds_read_b128 v[60:63], v1 offset:6640
	s_waitcnt lgkmcnt(3)
	v_fma_f32 v57, -v53, v2, v14
	s_waitcnt lgkmcnt(1)
	v_fma_f32 v10, -v53, v3, v15
	v_fma_f32 v14, -v53, v4, v54
	v_fma_f32 v15, -v53, v5, v55
	v_fma_f32 v54, -v53, v6, v56
	v_fma_f32 v55, -v53, v7, v58
	v_fma_f32 v56, -v53, v8, v59
	v_fma_f32 v58, -v53, v9, v64
	ds_read_b128 v[2:5], v1 offset:6896
	ds_read_b128 v[6:9], v1 offset:6912
	v_fma_f32 v59, -v57, v11, v10
	s_waitcnt lgkmcnt(1)
	v_fma_f32 v2, -v57, v12, v14
	v_fma_f32 v3, -v57, v13, v15
	v_fma_f32 v14, -v57, v60, v54
	v_fma_f32 v15, -v57, v61, v55
	v_fma_f32 v54, -v57, v62, v56
	v_fma_f32 v55, -v57, v63, v58
	ds_read_b128 v[10:13], v1 offset:7168
	ds_read_b128 v[62:65], v1 offset:7184
	v_fma_f32 v61, -v59, v4, v2
	s_waitcnt lgkmcnt(1)
	v_fma_f32 v10, -v59, v5, v3
	v_fma_f32 v6, -v59, v6, v14
	v_fma_f32 v7, -v59, v7, v15
	v_fma_f32 v8, -v59, v8, v54
	v_fma_f32 v9, -v59, v9, v55
	ds_read_b128 v[2:5], v1 offset:7456
	v_fma_f32 v60, -v61, v13, v10
	s_waitcnt lgkmcnt(1)
	v_fma_f32 v10, -v61, v62, v6
	v_fma_f32 v11, -v61, v63, v7
	v_fma_f32 v12, -v61, v64, v8
	v_fma_f32 v13, -v61, v65, v9
	ds_read_b128 v[6:9], v1 offset:7728
	s_waitcnt lgkmcnt(1)
	v_fma_f32 v58, -v60, v2, v10
	s_waitcnt lgkmcnt(0)
	v_fma_f32 v6, -v60, v3, v11
	v_fma_f32 v10, -v60, v4, v12
	v_fma_f32 v11, -v60, v5, v13
	ds_read_b128 v[2:5], v1 offset:8000
	v_fma_f32 v56, -v58, v7, v6
	s_waitcnt lgkmcnt(0)
	v_fma_f32 v2, -v58, v8, v10
	v_fma_f32 v3, -v58, v9, v11
	ds_read_b128 v[6:9], v1 offset:8272
	v_fma_f32 v55, -v56, v4, v2
	v_fma_f32 v1, -v56, v5, v3
	s_waitcnt lgkmcnt(0)
	v_fma_f32 v54, -v55, v9, v1
	v_add_u32_e32 v1, s1, v45
	v_cvt_pk_bf16_f32 v2, v17, v16
	ds_write_b16 v1, v2 offset:144
	ds_write_b16_d16_hi v1, v2 offset:288
	v_cvt_pk_bf16_f32 v2, v18, v19
	ds_write_b16 v1, v2 offset:432
	ds_write_b16_d16_hi v1, v2 offset:576
	v_cvt_pk_bf16_f32 v2, v20, v21
	ds_write_b16 v1, v2 offset:720
	ds_write_b16_d16_hi v1, v2 offset:864
	v_cvt_pk_bf16_f32 v2, v22, v23
	ds_write_b16 v1, v2 offset:1008
	ds_write_b16_d16_hi v1, v2 offset:1152
	v_cvt_pk_bf16_f32 v2, v25, v26
	ds_write_b16 v1, v2 offset:1296
	ds_write_b16_d16_hi v1, v2 offset:1440
	v_cvt_pk_bf16_f32 v2, v27, v28
	ds_write_b16 v1, v2 offset:1584
	ds_write_b16_d16_hi v1, v2 offset:1728
	v_cvt_pk_bf16_f32 v2, v29, v31
	ds_write_b16 v1, v2 offset:1872
	ds_write_b16_d16_hi v1, v2 offset:2016
	v_cvt_pk_bf16_f32 v2, v47, v30
	ds_write_b16 v1, v2 offset:2160
	ds_write_b16_d16_hi v1, v2 offset:2304
	v_cvt_pk_bf16_f32 v2, v46, v48
	ds_write_b16 v1, v2 offset:2448
	ds_write_b16_d16_hi v1, v2 offset:2592
	v_cvt_pk_bf16_f32 v2, v49, v50
	ds_write_b16 v1, v2 offset:2736
	ds_write_b16_d16_hi v1, v2 offset:2880
	v_cvt_pk_bf16_f32 v2, v51, v52
	ds_write_b16 v1, v2 offset:3024
	ds_write_b16_d16_hi v1, v2 offset:3168
	v_cvt_pk_bf16_f32 v2, v53, v57
	ds_write_b16 v1, v2 offset:3312
	ds_write_b16_d16_hi v1, v2 offset:3456
	v_cvt_pk_bf16_f32 v2, v59, v61
	ds_write_b16 v1, v2 offset:3600
	ds_write_b16_d16_hi v1, v2 offset:3744
	v_cvt_pk_bf16_f32 v2, v60, v58
	ds_write_b16 v1, v2 offset:3888
	ds_write_b16_d16_hi v1, v2 offset:4032
	v_cvt_pk_bf16_f32 v2, v56, v55
	ds_write_b16 v1, v2 offset:4176
	ds_write_b16_d16_hi v1, v2 offset:4320
	v_bfe_u32 v2, v54, 16, 1
	v_add3_u32 v2, v54, v2, s83
	ds_write_b16 v1, v197
	ds_write_b16_d16_hi v1, v2 offset:4464
	s_waitcnt lgkmcnt(0)
	v_mov_b32_e32 v1, 0x3f80
	ds_write_b16 v0, v1
	v_mov_b32_e32 v15, 0
	s_andn2_b64 vcc, exec, s[70:71]
	v_mov_b32_e32 v14, 0
	v_mov_b32_e32 v13, 0
	v_mov_b32_e32 v12, 0
	v_mov_b32_e32 v11, 0
	v_mov_b32_e32 v10, 0
	v_mov_b32_e32 v9, 0
	v_mov_b32_e32 v8, 0
	v_mov_b32_e32 v7, 0
	v_mov_b32_e32 v6, 0
	v_mov_b32_e32 v5, 0
	v_mov_b32_e32 v4, 0
	v_mov_b32_e32 v3, 0
	v_mov_b32_e32 v2, 0
	v_mov_b32_e32 v1, 0
	v_mov_b32_e32 v0, 0
	s_cbranch_vccnz .LBB0_293
	v_mul_u32_u24_e32 v0, 0x110, v42
	v_lshlrev_b32_e32 v1, 2, v24
	v_add3_u32 v62, s9, v0, v1
	ds_read_b128 v[0:3], v62 offset:8704
	ds_read_b128 v[4:7], v62 offset:8720
	v_cmp_gt_u32_e32 vcc, 32, v44
	v_cmp_eq_u32_e64 s[54:55], v24, v42
	s_waitcnt lgkmcnt(1)
	v_cvt_pk_bf16_f32 v0, v0, v1
	v_cvt_pk_bf16_f32 v1, v2, v3
	s_waitcnt lgkmcnt(0)
	v_cvt_pk_bf16_f32 v2, v4, v5
	v_mov_b32_e32 v4, v197
	v_cvt_pk_bf16_f32 v3, v6, v7
	v_cndmask_b32_e64 v5, 0, 1.0, s[54:55]
	v_cndmask_b32_e32 v4, v23, v4, vcc
	v_add_f32_e32 v4, v5, v4
	v_or_b32_e32 v5, 1, v24
	v_cmp_eq_u32_e64 s[54:55], v5, v42
	s_nop 1
	v_cndmask_b32_e64 v5, 0, 1.0, s[54:55]
	v_cndmask_b32_e32 v6, v25, v17, vcc
	v_add_f32_e32 v5, v5, v6
	v_or_b32_e32 v6, 2, v24
	v_cmp_eq_u32_e64 s[54:55], v6, v42
	v_cndmask_b32_e32 v7, v26, v16, vcc
	v_cndmask_b32_e32 v8, v27, v18, vcc
	v_cndmask_b32_e64 v6, 0, 1.0, s[54:55]
	v_add_f32_e32 v6, v6, v7
	v_or_b32_e32 v7, 3, v24
	v_cmp_eq_u32_e64 s[54:55], v7, v42
	v_cndmask_b32_e32 v9, v28, v19, vcc
	v_cndmask_b32_e32 v10, v29, v20, vcc
	v_cndmask_b32_e64 v7, 0, 1.0, s[54:55]
	v_add_f32_e32 v7, v7, v8
	v_or_b32_e32 v8, 4, v24
	v_cmp_eq_u32_e64 s[54:55], v8, v42
	v_cvt_pk_bf16_f32 v4, v4, v5
	v_cvt_pk_bf16_f32 v5, v6, v7
	s_nop 0
	v_cndmask_b32_e32 v11, v31, v21, vcc
	v_cndmask_b32_e64 v8, 0, 1.0, s[54:55]
	v_add_f32_e32 v8, v8, v9
	v_or_b32_e32 v9, 5, v24
	v_cmp_eq_u32_e64 s[54:55], v9, v42
	v_cndmask_b32_e32 v12, v47, v22, vcc
	s_nop 0
	v_cndmask_b32_e64 v9, 0, 1.0, s[54:55]
	v_add_f32_e32 v9, v9, v10
	v_or_b32_e32 v10, 6, v24
	v_cmp_eq_u32_e64 s[54:55], v10, v42
	v_cvt_pk_bf16_f32 v6, v8, v9
	s_nop 1
	v_cndmask_b32_e64 v10, 0, 1.0, s[54:55]
	v_add_f32_e32 v10, v10, v11
	v_or_b32_e32 v11, 7, v24
	v_cmp_eq_u32_e64 s[54:55], v11, v42
	s_nop 1
	v_cndmask_b32_e64 v11, 0, 1.0, s[54:55]
	v_add_f32_e32 v11, v11, v12
	v_cvt_pk_bf16_f32 v7, v10, v11
	ds_read_b128 v[16:19], v62 offset:8768
	ds_read_b128 v[20:23], v62 offset:8784
	s_waitcnt lgkmcnt(1)
	v_cvt_pk_bf16_f32 v16, v16, v17
	v_cvt_pk_bf16_f32 v17, v18, v19
	s_waitcnt lgkmcnt(0)
	v_cvt_pk_bf16_f32 v18, v20, v21
	v_or_b32_e32 v20, 16, v24
	v_cmp_eq_u32_e64 s[54:55], v20, v42
	v_cvt_pk_bf16_f32 v19, v22, v23
	s_nop 1
	v_cndmask_b32_e64 v20, 0, 1.0, s[54:55]
	v_cndmask_b32_e32 v21, v57, v30, vcc
	v_add_f32_e32 v20, v20, v21
	v_or_b32_e32 v21, 17, v24
	v_cmp_eq_u32_e64 s[54:55], v21, v42
	v_cndmask_b32_e32 v22, v59, v46, vcc
	v_cndmask_b32_e32 v23, v61, v48, vcc
	v_cndmask_b32_e64 v21, 0, 1.0, s[54:55]
	v_add_f32_e32 v21, v21, v22
	v_or_b32_e32 v22, 18, v24
	v_cmp_eq_u32_e64 s[54:55], v22, v42
	v_cndmask_b32_e32 v25, v60, v49, vcc
	v_mfma_f32_32x32x16_bf16 v[0:15], v[0:3], v[4:7], 0
	v_cndmask_b32_e64 v22, 0, 1.0, s[54:55]
	v_add_f32_e32 v22, v22, v23
	v_or_b32_e32 v23, 19, v24
	v_cmp_eq_u32_e64 s[54:55], v23, v42
	v_cndmask_b32_e32 v26, v58, v50, vcc
	v_cvt_pk_bf16_f32 v20, v20, v21
	s_nop 0
	v_cndmask_b32_e64 v23, 0, 1.0, s[54:55]
	v_add_f32_e32 v23, v23, v25
	v_or_b32_e32 v25, 20, v24
	v_cmp_eq_u32_e64 s[54:55], v25, v42
	v_cndmask_b32_e32 v27, v56, v51, vcc
	v_cndmask_b32_e32 v28, v55, v52, vcc
	v_cndmask_b32_e64 v25, 0, 1.0, s[54:55]
	v_add_f32_e32 v25, v25, v26
	v_or_b32_e32 v26, 21, v24
	v_cmp_eq_u32_e64 s[54:55], v26, v42
	v_cndmask_b32_e32 v29, v54, v53, vcc
	v_cvt_pk_bf16_f32 v21, v22, v23
	s_nop 0
	v_cndmask_b32_e64 v26, 0, 1.0, s[54:55]
	v_add_f32_e32 v26, v26, v27
	v_or_b32_e32 v27, 22, v24
	v_cmp_eq_u32_e64 s[54:55], v27, v42
	v_cvt_pk_bf16_f32 v22, v25, v26
	s_nop 1
	v_cndmask_b32_e64 v27, 0, 1.0, s[54:55]
	v_add_f32_e32 v27, v27, v28
	v_or_b32_e32 v28, 23, v24
	v_cmp_eq_u32_e32 vcc, v28, v42
	s_nop 1
	v_cndmask_b32_e64 v28, 0, 1.0, vcc
	v_add_f32_e32 v28, v28, v29
	v_cvt_pk_bf16_f32 v23, v27, v28
	s_nop 0
	v_mfma_f32_32x32x16_bf16 v[0:15], v[16:19], v[20:23], v[0:15]
.LBB0_293:
	s_waitcnt lgkmcnt(0)
	s_barrier
	s_andn2_b64 vcc, exec, s[70:71]
	v_mul_u32_u24_e32 v46, 0x90, v42
	s_cbranch_vccnz .LBB0_295
	s_add_i32 s9, 0, 0x1a400
	v_add3_u32 v16, s9, v46, v24
	v_add_u32_e32 v47, 0x1000, v16
	ds_read2_b64 v[16:19], v47 offset0:72 offset1:74
	s_nop 3
	v_cvt_pk_bf16_f32 v0, v0, v1
	v_cvt_pk_bf16_f32 v1, v2, v3
	v_cvt_pk_bf16_f32 v2, v4, v5
	v_cvt_pk_bf16_f32 v3, v6, v7
	v_cvt_pk_bf16_f32 v4, v8, v9
	v_cvt_pk_bf16_f32 v5, v10, v11
	v_cvt_pk_bf16_f32 v6, v12, v13
	v_cvt_pk_bf16_f32 v7, v14, v15
	s_waitcnt lgkmcnt(0)
	v_mfma_f32_32x32x16_bf16 v[16:31], v[16:19], v[0:3], 0
	ds_read2_b64 v[0:3], v47 offset0:76 offset1:78
	v_mul_u32_u24_e32 v8, 0x240, v37
	v_add3_u32 v8, s9, v8, v45
	s_waitcnt lgkmcnt(0)
	v_mfma_f32_32x32x16_bf16 v[16:31], v[0:3], v[4:7], v[16:31]
	s_nop 11
	v_xor_b32_e32 v0, 0x80000000, v16
	v_xor_b32_e32 v1, 0x80000000, v17
	v_xor_b32_e32 v2, 0x80000000, v18
	v_xor_b32_e32 v3, 0x80000000, v19
	v_bfe_u32 v4, v0, 16, 1
	v_bfe_u32 v5, v1, 16, 1
	v_bfe_u32 v6, v2, 16, 1
	v_add3_u32 v0, v0, v4, s83
	v_add3_u32 v1, v1, v5, s83
	v_add3_u32 v2, v2, v6, s83
	ds_write_b16_d16_hi v8, v0 offset:4608
	ds_write_b16_d16_hi v8, v1 offset:4752
	ds_write_b16_d16_hi v8, v2 offset:4896
	v_xor_b32_e32 v0, 0x80000000, v20
	v_cvt_pk_bf16_f32 v0, v3, v0
	ds_write_b16 v8, v0 offset:5040
	ds_write_b16_d16_hi v8, v0 offset:5760
	v_xor_b32_e32 v0, 0x80000000, v21
	v_xor_b32_e32 v1, 0x80000000, v22
	v_cvt_pk_bf16_f32 v0, v0, v1
	ds_write_b16 v8, v0 offset:5904
	ds_write_b16_d16_hi v8, v0 offset:6048
	v_xor_b32_e32 v0, 0x80000000, v23
	v_xor_b32_e32 v1, 0x80000000, v24
	v_cvt_pk_bf16_f32 v0, v0, v1
	ds_write_b16 v8, v0 offset:6192
	ds_write_b16_d16_hi v8, v0 offset:6912
	v_xor_b32_e32 v0, 0x80000000, v25
	v_xor_b32_e32 v1, 0x80000000, v26
	v_cvt_pk_bf16_f32 v0, v0, v1
	ds_write_b16 v8, v0 offset:7056
	ds_write_b16_d16_hi v8, v0 offset:7200
	v_xor_b32_e32 v0, 0x80000000, v27
	v_xor_b32_e32 v1, 0x80000000, v28
	v_cvt_pk_bf16_f32 v0, v0, v1
	ds_write_b16 v8, v0 offset:7344
	ds_write_b16_d16_hi v8, v0 offset:8064
	v_xor_b32_e32 v0, 0x80000000, v29
	v_xor_b32_e32 v1, 0x80000000, v30
	v_cvt_pk_bf16_f32 v0, v0, v1
	ds_write_b16 v8, v0 offset:8208
	ds_write_b16_d16_hi v8, v0 offset:8352
	v_xor_b32_e32 v0, 0x80000000, v31
	v_bfe_u32 v1, v0, 16, 1
	v_add3_u32 v0, v0, v1, s83
	ds_write_b16_d16_hi v8, v0 offset:8496
